# stagger GEMM1 start in 4 groups by (bid>>3)&3, 2x s_sleep127 per step
# baseline (speedup 1.0000x reference)
; #define PG8_BAR __builtin_amdgcn_s_barrier()
;     __device__ __forceinline__ void acc_init(f32x4 (&ini)[2][2], const Unit& u) const {
;         int t__ = threadIdx.x; asm volatile("" : "+v"(t__)); const int wid__ = __builtin_amdgcn_readfirstlane(t__ >> 6), wc = wid__ & 3, fq = (t__ & 63) >> 4;
; template <class Epi, class Sched, bool ALIGN_EPI = false, bool SP2 = false>
; __device__ __forceinline__ void gemm_phase(PG8_LAS unsigned char* lds, const Gemm g, const Sched& S, const Epi& E) {
;     int tid_ = threadIdx.x; asm volatile("" : "+v"(tid_));
;     const int tid = tid_, wid = __builtin_amdgcn_readfirstlane(tid >> 6), lane = tid & 63, wr = wid >> 2, wc = wid & 3, fr = lane & 15, fq = lane >> 4;
;     int K_ = g.K; asm volatile("" : "+s"(K_));
;     const int K = K_, nt = K / BK;
;     unsigned voffA[2], voffB[2];
; #pragma unroll
;     for (int i = 0; i < 2; ++i) { int R, C; stage_rc(tid * 16 + i * 8192, R, C); const int Rb = Epi::PERM ? ((R & ~31) + perm32(R & 31)) : R;
;         voffA[i] = (unsigned)(R * K + C) * 2u; voffB[i] = (unsigned)(Rb * K + C) * 2u; }
;     const size_t kstep = (size_t)(BK * 2);
;     const size_t hstep = (size_t)HALF * K * 2;
;     const size_t tstep = 2 * hstep;
;     const unsigned ldsw = (unsigned)wid * 1024u;
;     const int aoff = lds_byte(wr * 64 + fr, fq * 8), boff = lds_byte(wc * 32 + fr, fq * 8);
;     ...
;     Unit cur, nxt; int ui = 0;
;     if (!S.next(0, cur)) return;
;     f32x4 acc[2][2][4][2];
;     f32x4 ini[2][2];
; #pragma unroll
;     for (int b = 0; b < 2; ++b)
; #pragma unroll
;         for (int n = 0; n < 2; ++n) ini[b][n] = (f32x4){0.f, 0.f, 0.f, 0.f};
;     if constexpr (Epi::ACC_INIT) E.acc_init(ini, cur);
; #pragma unroll
;     for (int a = 0; a < 2; ++a)
; #pragma unroll
;         for (int b = 0; b < 2; ++b)
; #pragma unroll
;             for (int m = 0; m < 4; ++m)
; #pragma unroll
;                 for (int n = 0; n < 2; ++n) acc[a][b][m][n] = ini[b][n];
;     bf16x8 At[4][2], B0[2][2], B1[2][2];
;     const char* cA = (const char*)g.A + (size_t)cur.pm * tstep; const char* cB = (const char*)g.Bt + (size_t)cur.pn * tstep;
;     S.a_ready(cur);
;     if constexpr (SP2) {
;         PG8_STAGE(PG8_SB(0, 0), cB, voffB); PG8_STAGE(PG8_SB(0, 1), cB + hstep, voffB); PG8_STAGE(PG8_SA(0, 0), cA, voffA); PG8_STAGE(PG8_SA(0, 1), cA + hstep, voffA);
;         if (wr == 1) PG8_BAR;
;         PG8_WAIT_V(2); PG8_BAR;
.LBB0_386:
	s_and_b64 vcc, exec, s[38:39]
	s_cbranch_vccz .LBB0_416
	v_readlane_b32 s12, v253, 29
	s_waitcnt vmcnt(0)
	v_mov_b32_e32 v16, v212
	v_readlane_b32 s13, v253, 30
	s_movk_i32 s38, 0x400
	v_readfirstlane_b32 s50, v16
	s_andn2_b64 vcc, exec, s[12:13]
	s_cbranch_vccnz .LBB0_416
	s_lshr_b32 s98, s2, 3
	s_and_b32 s98, s98, 3
	s_mul_i32 s98, s98, 2
	s_cmp_eq_u32 s98, 0
	s_cbranch_scc1 .Lstag1_done
.Lstag1_loop:
	s_sleep 127
	s_sub_u32 s98, s98, 1
	s_cmp_lg_u32 s98, 0
	s_cbranch_scc1 .Lstag1_loop
.Lstag1_done:
	s_waitcnt vmcnt(0)
	v_lshlrev_b32_e32 v0, 4, v16
	s_waitcnt lgkmcnt(0)
	v_add_u32_e32 v1, 0x2000, v0
	v_ashrrev_i32_e32 v2, 31, v1
	v_lshrrev_b32_e32 v2, 22, v2
	v_add_u32_e32 v2, v1, v2
	s_ashr_i32 s73, s72, 31
	v_ashrrev_i32_e32 v2, 10, v2
	s_lshl_b64 s[12:13], s[72:73], 3
	v_readlane_b32 s16, v253, 0
	s_waitcnt lgkmcnt(2)
	v_mul_i32_i24_e32 v3, 0x400, v2
	v_readlane_b32 s17, v253, 1
	s_add_u32 s12, s16, s12
	v_sub_u32_e32 v1, v1, v3
	s_addc_u32 s13, s17, s13
	v_lshrrev_b32_e32 v3, 4, v1
	s_load_dwordx2 s[12:13], s[12:13], 0x10
	v_bitop3_b32 v1, v3, v1, 32 bitop3:0x6c
	v_ashrrev_i32_e32 v3, 31, v1
	v_lshrrev_b32_e32 v3, 26, v3
	v_add_u32_e32 v3, v1, v3
	s_waitcnt vmcnt(0) lgkmcnt(0)
	v_lshlrev_b32_e32 v5, 3, v2
	s_mul_i32 s0, s80, 0x6020
	v_ashrrev_i32_e32 v4, 6, v3
	v_and_b32_e32 v5, -16, v5
	v_lshlrev_b32_e32 v2, 5, v2
	s_mul_hi_i32 s6, s80, 0x6020
	s_add_u32 s0, s12, s0
	v_add_u32_e32 v5, v4, v5
	v_and_b32_e32 v17, 32, v2
	v_and_b32_e32 v2, 0xc0, v3
	s_addc_u32 s6, s13, s6
	v_and_b32_e32 v4, 3, v4
	s_mov_b32 s13, 0x7fffffe0
	v_lshrrev_b32_e32 v6, 2, v5
	v_lshlrev_b32_e32 v7, 1, v5
	v_sub_u32_e32 v1, v1, v2
	v_and_or_b32 v4, v5, s13, v4
	v_and_b32_e32 v6, 4, v6
	v_and_b32_e32 v7, 24, v7
	v_ashrrev_i16_sdwa v1, v222, sext(v1) dst_sel:DWORD dst_unused:UNUSED_PAD src0_sel:DWORD src1_sel:BYTE_0
	v_or3_b32 v4, v4, v6, v7
	v_bfe_i32 v18, v1, 0, 16
	v_mul_lo_u32 v4, v4, s38
	v_add_u32_e32 v1, v17, v18
	v_mul_lo_u32 v19, v5, s38
	v_add_lshl_u32 v130, v4, v1, 1
	v_add_lshl_u32 v132, v1, v19, 1
	v_bfe_i32 v1, v16, 27, 1
	v_lshrrev_b32_e32 v1, 22, v1
	v_add_u32_e32 v1, v0, v1
	v_and_b32_e32 v1, 0xfffffc00, v1
	v_sub_u32_e32 v0, v0, v1
	v_lshrrev_b32_e32 v1, 4, v0
	v_ashrrev_i32_e32 v3, 31, v16
	v_bitop3_b32 v0, v1, v0, 32 bitop3:0x6c
	v_lshrrev_b32_e32 v3, 26, v3
	v_ashrrev_i32_e32 v1, 31, v0
	v_add_u32_e32 v3, v16, v3
	v_lshrrev_b32_e32 v1, 26, v1
	v_ashrrev_i32_e32 v3, 6, v3
	v_add_u32_e32 v1, v0, v1
	v_lshlrev_b32_e32 v4, 3, v3
	v_ashrrev_i32_e32 v2, 6, v1
	v_and_b32_e32 v4, -16, v4
	v_add_u32_e32 v4, v2, v4
	v_and_b32_e32 v1, 0xc0, v1
	v_writelane_b32 v252, s76, 50
	v_and_b32_e32 v2, 3, v2
	v_lshrrev_b32_e32 v5, 2, v4
	v_lshlrev_b32_e32 v6, 1, v4
	v_sub_u32_e32 v0, v0, v1
	v_writelane_b32 v252, s77, 51
	s_ashr_i32 s48, s50, 6
	s_ashr_i32 s39, s38, 31
	v_and_or_b32 v2, v4, s13, v2
	v_and_b32_e32 v5, 4, v5
	v_and_b32_e32 v6, 24, v6
	v_lshlrev_b32_e32 v3, 5, v3
	v_ashrrev_i16_sdwa v0, v222, sext(v0) dst_sel:DWORD dst_unused:UNUSED_PAD src0_sel:DWORD src1_sel:BYTE_0
	s_ashr_i32 s49, s50, 8
	s_lshl_b64 s[42:43], s[38:39], 8
	s_lshl_b64 s[44:45], s[38:39], 9
	s_lshl_b32 s12, s48, 10
	v_or3_b32 v2, v2, v5, v6
	v_and_b32_e32 v20, 32, v3
	v_bfe_i32 v21, v0, 0, 16
	v_readlane_b32 s16, v252, 40
	v_mul_lo_u32 v2, v2, s38
	v_add_u32_e32 v0, v20, v21
	v_mul_lo_u32 v22, v4, s38
	v_readlane_b32 s17, v252, 41
	s_add_u32 s16, s0, s16
	v_add_lshl_u32 v96, v2, v0, 1
	v_add_lshl_u32 v134, v0, v22, 1
	v_mov_b32_e32 v0, v212
	s_addc_u32 s17, s6, s17
	v_readlane_b32 s20, v252, 42
	s_add_u32 s16, s16, s20
	v_readfirstlane_b32 s13, v0
	s_addc_u32 s17, s17, 0
	s_lshl_b32 s13, s13, 1
	s_and_b32 s13, s13, 0x180
	s_add_u32 s16, s16, s13
	v_lshlrev_b32_e32 v0, 1, v0
	s_addc_u32 s17, s17, 0
	v_and_b32_e32 v4, 0x60, v0
	v_readlane_b32 s13, v252, 37
	v_readlane_b32 s20, v252, 36
	global_load_dwordx4 v[8:11], v4, s[16:17] offset:16
	global_load_dwordx4 v[12:15], v4, s[16:17]
	global_load_dwordx4 v[0:3], v4, s[16:17] offset:528
	s_nop 0
	global_load_dwordx4 v[4:7], v4, s[16:17] offset:512
	s_mul_i32 s13, s44, s13
	s_mul_hi_u32 s16, s44, s20
	s_add_i32 s13, s16, s13
	s_lshr_b64 s[16:17], s[38:39], 23
	v_readlane_b32 s24, v252, 34
	s_mul_i32 s17, s16, s20
	v_readlane_b32 s25, v252, 35
	s_add_i32 s21, s13, s17
	s_mul_i32 s13, s44, s25
	s_mul_hi_u32 s17, s44, s24
	s_add_i32 s13, s17, s13
	s_mul_i32 s16, s16, s24
	s_add_i32 s13, s13, s16
	s_mul_i32 s16, s44, s24
	v_readlane_b32 s24, v253, 27
	v_readlane_b32 s25, v253, 28
	s_add_u32 s62, s24, s16
	s_addc_u32 s63, s25, s13
	s_add_i32 s13, s12, 0x10000
	s_add_i32 s16, s12, 0x12000
	s_mov_b32 m0, s13
	s_add_u32 s40, s62, s42
	s_mul_i32 s22, s44, s20
	global_load_lds_dwordx4 v96, s[62:63]
	s_mov_b32 m0, s16
	s_addc_u32 s41, s63, s43
	s_add_i32 s17, s12, 0x14000
	s_add_i32 s20, s12, 0x16000
	global_load_lds_dwordx4 v130, s[62:63]
	s_mov_b32 m0, s17
	s_add_u32 s60, s82, s22
	global_load_lds_dwordx4 v96, s[40:41]
	s_mov_b32 m0, s20
	s_addc_u32 s61, s83, s21
	s_add_i32 s21, s12, 0x2000
	global_load_lds_dwordx4 v130, s[40:41]
	s_mov_b32 m0, s12
	s_add_u32 s46, s60, s42
	global_load_lds_dwordx4 v134, s[60:61]
	s_mov_b32 m0, s21
	s_addc_u32 s47, s61, s43
	s_add_i32 s22, s12, 0x4000
	global_load_lds_dwordx4 v132, s[60:61]
	s_mov_b32 m0, s22
	s_add_i32 s23, s12, 0x6000
	global_load_lds_dwordx4 v134, s[46:47]
	s_mov_b32 m0, s23
	s_cmp_eq_u32 s49, 1
	global_load_lds_dwordx4 v132, s[46:47]
	s_mov_b32 s86, s72
	s_cselect_b64 s[46:47], -1, 0
	s_cmp_lg_u32 s49, 1
	s_cbranch_scc1 .LBB0_390
	s_barrier

; __global__ void __launch_bounds__(512, 2) mega_fwd(Args args) {
;     __shared__ __attribute__((aligned(16))) unsigned char lds_raw[LDS_BYTES];
	.amdhsa_kernel _Z8mega_fwd4Args
		.amdhsa_group_segment_fixed_size 147456
		.amdhsa_private_segment_fixed_size 0
		.amdhsa_kernarg_size 448
		.amdhsa_user_sgpr_count 2
		.amdhsa_user_sgpr_dispatch_ptr 0
		.amdhsa_user_sgpr_queue_ptr 0
		.amdhsa_user_sgpr_kernarg_segment_ptr 1
		.amdhsa_user_sgpr_dispatch_id 0
		.amdhsa_user_sgpr_kernarg_preload_length 0
		.amdhsa_user_sgpr_kernarg_preload_offset 0
		.amdhsa_user_sgpr_private_segment_size 0
		.amdhsa_uses_dynamic_stack 0
		.amdhsa_enable_private_segment 0
		.amdhsa_system_sgpr_workgroup_id_x 1
		.amdhsa_system_sgpr_workgroup_id_y 0
		.amdhsa_system_sgpr_workgroup_id_z 0
		.amdhsa_system_sgpr_workgroup_info 0
		.amdhsa_system_vgpr_workitem_id 2
		.amdhsa_next_free_vgpr 254
		.amdhsa_next_free_sgpr 102
		.amdhsa_accum_offset 256
		.amdhsa_reserve_vcc 1
		.amdhsa_float_round_mode_32 0
		.amdhsa_float_round_mode_16_64 0
		.amdhsa_float_denorm_mode_32 3
		.amdhsa_float_denorm_mode_16_64 3
		.amdhsa_dx10_clamp 1
		.amdhsa_ieee_mode 1
		.amdhsa_fp16_overflow 0
		.amdhsa_tg_split 0
		.amdhsa_exception_fp_ieee_invalid_op 0
		.amdhsa_exception_fp_denorm_src 0
		.amdhsa_exception_fp_ieee_div_zero 0
		.amdhsa_exception_fp_ieee_overflow 0
		.amdhsa_exception_fp_ieee_underflow 0
		.amdhsa_exception_fp_ieee_inexact 0
		.amdhsa_exception_int_div_zero 0
	.end_amdhsa_kernel

; __global__ void __launch_bounds__(512, 2) mega_fwd(Args args) {
;     __shared__ __attribute__((aligned(16))) unsigned char lds_raw[LDS_BYTES];
amdhsa.kernels:
  - .agpr_count:     0
    .args:
      - .offset:         0
        .size:           192
        .value_kind:     by_value
      - .offset:         192
        .size:           4
        .value_kind:     hidden_block_count_x
      - .offset:         196
        .size:           4
        .value_kind:     hidden_block_count_y
      - .offset:         200
        .size:           4
        .value_kind:     hidden_block_count_z
      - .offset:         204
        .size:           2
        .value_kind:     hidden_group_size_x
      - .offset:         206
        .size:           2
        .value_kind:     hidden_group_size_y
      - .offset:         208
        .size:           2
        .value_kind:     hidden_group_size_z
      - .offset:         210
        .size:           2
        .value_kind:     hidden_remainder_x
      - .offset:         212
        .size:           2
        .value_kind:     hidden_remainder_y
      - .offset:         214
        .size:           2
        .value_kind:     hidden_remainder_z
      - .offset:         232
        .size:           8
        .value_kind:     hidden_global_offset_x
      - .offset:         240
        .size:           8
        .value_kind:     hidden_global_offset_y
      - .offset:         248
        .size:           8
        .value_kind:     hidden_global_offset_z
      - .offset:         256
        .size:           2
        .value_kind:     hidden_grid_dims
      - .offset:         280
        .size:           8
        .value_kind:     hidden_multigrid_sync_arg
    .group_segment_fixed_size: 147456
    .kernarg_segment_align: 8
    .kernarg_segment_size: 448
    .language:       OpenCL C
    .language_version:
      - 2
      - 0
    .max_flat_workgroup_size: 512
    .name:           _Z8mega_fwd4Args
    .private_segment_fixed_size: 0
    .sgpr_count:     108
    .sgpr_spill_count: 129
    .symbol:         _Z8mega_fwd4Args.kd
    .uniform_work_group_size: 1
    .uses_dynamic_stack: false
    .vgpr_count:     254
    .vgpr_spill_count: 0
    .wavefront_size: 64
